# v83 + attention: static priority 2 for waves 4..7 (mirror of the waves 0..3 variant)
# baseline (speedup 1.0000x reference)
.LBB0_1330:
	s_or_b64 exec, exec, s[6:7]
	v_mov_b32_e32 v1, v192
	s_waitcnt lgkmcnt(0)
	s_barrier
	s_cmpk_gt_i32 s2, 0x1ff
	v_readfirstlane_b32 s6, v1
	s_cbranch_scc1 .LBB0_1349
	v_ashrrev_i32_e32 v193, 4, v1
	v_add_u32_e32 v194, 32, v193
	s_ashr_i32 s10, s6, 6
	s_cmp_lt_u32 s6, 0x100
	s_cbranch_scc1 .Lattn_prio_lo
	s_setprio 2
